# residual GEMM epilogue (out-proj and W2) rewritten by hand: lane-pair DPP exchange so each residual load and store covers whole 128-byte lines, second-half residual loads issued early
# speedup vs baseline: 1.3612x; 1.0059x over previous
; #define PG8_STAGE(bufoff, gbase, voff) do { _Pragma("unroll") for (int _i = 0; _i < 2; ++_i) \
;         __builtin_amdgcn_global_load_lds((const unsigned*)((const char*)(gbase) + (voff)[_i]), (PG8_LAS unsigned*)(lds + (bufoff) + ldsw + _i * 8192), 16, 0, 0); } while (0)
; #define PG8_LDA(dst, b, h) do { _Pragma("unroll") for (int m = 0; m < 4; ++m) _Pragma("unroll") for (int k = 0; k < 2; ++k) dst[m][k] = *(const PG8_LAS bf16x8*)(lds + PG8_SA(b, h) + aoff + m * 2048 + k * 1024); } while (0)
; #define PG8_LDB(dst, b, h) do { _Pragma("unroll") for (int n = 0; n < 2; ++n) _Pragma("unroll") for (int k = 0; k < 2; ++k) dst[n][k] = *(const PG8_LAS bf16x8*)(lds + PG8_SB(b, h) + boff + n * 2048 + k * 1024); } while (0)
; #define PG8_WAIT_V(n) asm volatile("s_waitcnt vmcnt(" #n ")" ::: "memory")
; #define PG8_WAIT_L(n) asm volatile("s_waitcnt lgkmcnt(" #n ")" ::: "memory")
; #define PG8_BAR __builtin_amdgcn_s_barrier()
; #define PG8_SCHED __builtin_amdgcn_sched_barrier(0)
; template <class Epi, class Sched>
; __device__ __forceinline__ void gemm_phase(PG8_LAS unsigned char* lds, const Gemm g, const Sched& S, const Epi& E, const int tid) {
;     ...
;         for (int t = 0; t < nt; t += 2) {
;             const bool last = (t == nt - 2);
;             const char* a1 = cA + (size_t)(t + 1) * kstep;
;             const char* a2 = last ? nA : cA + (size_t)(t + 2) * kstep; const char* b2 = last ? nB : cB + (size_t)(t + 2) * kstep;
;             const char* a3 = a2 + kstep; const char* b3 = b2 + kstep;
;             if (last && has_next) S.a_ready(nxt);
;             PG8_LDB(B0, 0, 0); PG8_SCHED; PG8_LDA(At, 0, 0); PG8_STAGE(PG8_SA(1, 1), a1 + hstep, voffA);
;             PG8_WAIT_L(8); PG8_BAR; PG8_WAIT_L(0); PG8_MMA(0, 0, At, B0); PG8_BAR; PG8_SCHED;
;             PG8_LDB(B1, 0, 1); PG8_STAGE(PG8_SB(0, 0), b2, voffB);
;             PG8_BAR; PG8_WAIT_L(0); PG8_MMA(0, 1, At, B1); PG8_BAR;
;             PG8_LDA(At, 0, 1); PG8_STAGE(PG8_SA(0, 0), a2, voffA);
;             PG8_BAR; PG8_WAIT_L(0); PG8_MMA(1, 0, At, B0); PG8_BAR; PG8_SCHED;
;             PG8_STAGE(PG8_SB(0, 1), b2 + hstep, voffB);
;             PG8_WAIT_V(6); PG8_BAR; PG8_MMA(1, 1, At, B1); PG8_BAR;
;             PG8_LDB(B0, 1, 0); PG8_SCHED; PG8_LDA(At, 1, 0); PG8_STAGE(PG8_SA(0, 1), a2 + hstep, voffA);
;             PG8_WAIT_L(8); PG8_BAR; PG8_WAIT_L(0); PG8_MMA(0, 0, At, B0); PG8_BAR; PG8_SCHED;
.LBB0_475:
	s_add_i32 s94, s56, 2
	s_add_u32 s72, s68, 0x80
	s_addc_u32 s57, s69, 0
	s_add_i32 s95, 0, 0x10000
	v_add_u32_e32 v148, s95, v157
	ds_read_b128 v[130:133], v148
	ds_read_b128 v[134:137], v148 offset:1024
	ds_read_b128 v[138:141], v148 offset:2048
	ds_read_b128 v[148:151], v148 offset:3072
	s_cmp_eq_u32 s63, s56
	s_cselect_b32 s56, s4, s72
	s_cselect_b32 s57, s5, s57
	s_cselect_b32 s73, s7, s91
	s_cselect_b32 s72, s6, s90
	v_lshl_add_u64 v[188:189], s[68:69], 0, v[144:145]
	s_add_i32 m0, s0, 0xc000
	ds_read_b128 v[152:155], v159
	ds_read_b128 v[160:163], v159 offset:1024
	ds_read_b128 v[164:167], v159 offset:2048
	ds_read_b128 v[168:171], v159 offset:3072
	ds_read_b128 v[172:175], v159 offset:4096
	ds_read_b128 v[176:179], v159 offset:5120
	ds_read_b128 v[180:183], v159 offset:6144
	ds_read_b128 v[184:187], v159 offset:7168
	global_load_lds_dwordx4 v[188:189], off
	v_lshl_add_u64 v[188:189], s[68:69], 0, v[146:147]
	s_add_i32 m0, s0, 0xe000
	s_nop 0
	global_load_lds_dwordx4 v[188:189], off
	s_waitcnt lgkmcnt(8)
	s_barrier
	s_waitcnt lgkmcnt(0)
	s_setprio 1
	s_waitcnt lgkmcnt(0)
	v_mfma_f32_16x16x32_bf16 v[126:129], v[130:133], v[152:155], v[126:129]
	v_mfma_f32_16x16x32_bf16 v[122:125], v[138:141], v[152:155], v[122:125]
	v_mfma_f32_16x16x32_bf16 v[118:121], v[130:133], v[164:167], v[118:121]
	v_mfma_f32_16x16x32_bf16 v[106:109], v[138:141], v[164:167], v[106:109]
	v_mfma_f32_16x16x32_bf16 v[102:105], v[130:133], v[172:175], v[102:105]
	v_mfma_f32_16x16x32_bf16 v[90:93], v[138:141], v[172:175], v[90:93]
	v_mfma_f32_16x16x32_bf16 v[86:89], v[130:133], v[180:183], v[86:89]
	v_mfma_f32_16x16x32_bf16 v[74:77], v[138:141], v[180:183], v[74:77]
	v_mfma_f32_16x16x32_bf16 v[126:129], v[134:137], v[160:163], v[126:129]
	v_mfma_f32_16x16x32_bf16 v[122:125], v[148:151], v[160:163], v[122:125]
	v_mfma_f32_16x16x32_bf16 v[118:121], v[134:137], v[168:171], v[118:121]
	v_mfma_f32_16x16x32_bf16 v[106:109], v[148:151], v[168:171], v[106:109]
	v_mfma_f32_16x16x32_bf16 v[102:105], v[134:137], v[176:179], v[102:105]
	v_mfma_f32_16x16x32_bf16 v[90:93], v[148:151], v[176:179], v[90:93]
	v_mfma_f32_16x16x32_bf16 v[86:89], v[134:137], v[184:187], v[86:89]
	v_mfma_f32_16x16x32_bf16 v[74:77], v[148:151], v[184:187], v[74:77]
	s_setprio 0
	s_barrier
	s_add_i32 s96, 0, 0x14000
	v_add_u32_e32 v196, s96, v157
	s_add_i32 s95, s95, s45
	ds_read_b128 v[188:191], v196
	ds_read_b128 v[192:195], v196 offset:1024
	ds_read_b128 v[200:203], v196 offset:2048
	ds_read_b128 v[216:219], v196 offset:3072
	v_lshl_add_u64 v[196:197], s[72:73], 0, v[0:1]
	s_mov_b32 m0, s95
	v_lshl_add_u64 v[198:199], s[72:73], 0, v[142:143]
	global_load_lds_dwordx4 v[196:197], off
	s_add_i32 m0, s95, 0x2000
	s_nop 0
	global_load_lds_dwordx4 v[198:199], off
	s_barrier
	s_waitcnt lgkmcnt(0)
	s_setprio 1
	s_waitcnt lgkmcnt(0)
	v_mfma_f32_16x16x32_bf16 v[114:117], v[188:191], v[152:155], v[114:117]
	v_mfma_f32_16x16x32_bf16 v[110:113], v[200:203], v[152:155], v[110:113]
	v_mfma_f32_16x16x32_bf16 v[98:101], v[188:191], v[164:167], v[98:101]
	v_mfma_f32_16x16x32_bf16 v[94:97], v[200:203], v[164:167], v[94:97]
	v_mfma_f32_16x16x32_bf16 v[82:85], v[188:191], v[172:175], v[82:85]
	v_mfma_f32_16x16x32_bf16 v[78:81], v[200:203], v[172:175], v[78:81]
	v_mfma_f32_16x16x32_bf16 v[70:73], v[188:191], v[180:183], v[70:73]
	v_mfma_f32_16x16x32_bf16 v[66:69], v[200:203], v[180:183], v[66:69]
	v_mfma_f32_16x16x32_bf16 v[114:117], v[192:195], v[160:163], v[114:117]
	v_mfma_f32_16x16x32_bf16 v[110:113], v[216:219], v[160:163], v[110:113]
	v_mfma_f32_16x16x32_bf16 v[98:101], v[192:195], v[168:171], v[98:101]
	v_mfma_f32_16x16x32_bf16 v[94:97], v[216:219], v[168:171], v[94:97]
	v_mfma_f32_16x16x32_bf16 v[82:85], v[192:195], v[176:179], v[82:85]
	v_mfma_f32_16x16x32_bf16 v[78:81], v[216:219], v[176:179], v[78:81]
	v_mfma_f32_16x16x32_bf16 v[70:73], v[192:195], v[184:187], v[70:73]
	v_mfma_f32_16x16x32_bf16 v[66:69], v[216:219], v[184:187], v[66:69]
	s_setprio 0
	s_mov_b32 m0, s0
	v_lshl_add_u64 v[220:221], s[56:57], 0, v[0:1]
	s_barrier
	ds_read_b128 v[152:155], v159 offset:16384
	ds_read_b128 v[160:163], v159 offset:17408
	ds_read_b128 v[164:167], v159 offset:18432
	ds_read_b128 v[168:171], v159 offset:19456
	ds_read_b128 v[172:175], v159 offset:20480
	ds_read_b128 v[176:179], v159 offset:21504
	ds_read_b128 v[180:183], v159 offset:22528
	ds_read_b128 v[184:187], v159 offset:23552
	global_load_lds_dwordx4 v[220:221], off
	v_lshl_add_u64 v[222:223], s[56:57], 0, v[142:143]
	s_mov_b32 m0, s1
	s_nop 0
	global_load_lds_dwordx4 v[222:223], off
	s_barrier
	s_waitcnt lgkmcnt(0)
	s_setprio 1
	s_waitcnt lgkmcnt(0)
	v_mfma_f32_16x16x32_bf16 v[62:65], v[130:133], v[152:155], v[62:65]
	v_mfma_f32_16x16x32_bf16 v[58:61], v[138:141], v[152:155], v[58:61]
	v_mfma_f32_16x16x32_bf16 v[54:57], v[130:133], v[164:167], v[54:57]
	v_mfma_f32_16x16x32_bf16 v[42:45], v[138:141], v[164:167], v[42:45]
	v_mfma_f32_16x16x32_bf16 v[38:41], v[130:133], v[172:175], v[38:41]
	v_mfma_f32_16x16x32_bf16 v[26:29], v[138:141], v[172:175], v[26:29]
	v_mfma_f32_16x16x32_bf16 v[22:25], v[130:133], v[180:183], v[22:25]
	v_mfma_f32_16x16x32_bf16 v[10:13], v[138:141], v[180:183], v[10:13]
	v_mfma_f32_16x16x32_bf16 v[62:65], v[134:137], v[160:163], v[62:65]
	v_mfma_f32_16x16x32_bf16 v[58:61], v[148:151], v[160:163], v[58:61]
	v_mfma_f32_16x16x32_bf16 v[54:57], v[134:137], v[168:171], v[54:57]
	v_mfma_f32_16x16x32_bf16 v[42:45], v[148:151], v[168:171], v[42:45]
	v_mfma_f32_16x16x32_bf16 v[38:41], v[134:137], v[176:179], v[38:41]
	v_mfma_f32_16x16x32_bf16 v[26:29], v[148:151], v[176:179], v[26:29]
	v_mfma_f32_16x16x32_bf16 v[22:25], v[134:137], v[184:187], v[22:25]
	v_mfma_f32_16x16x32_bf16 v[10:13], v[148:151], v[184:187], v[10:13]
	s_setprio 0
	s_barrier
; #define PG8_STAGE(bufoff, gbase, voff) do { _Pragma("unroll") for (int _i = 0; _i < 2; ++_i) \
;         __builtin_amdgcn_global_load_lds((const unsigned*)((const char*)(gbase) + (voff)[_i]), (PG8_LAS unsigned*)(lds + (bufoff) + ldsw + _i * 8192), 16, 0, 0); } while (0)
; #define PG8_LDA(dst, b, h) do { _Pragma("unroll") for (int m = 0; m < 4; ++m) _Pragma("unroll") for (int k = 0; k < 2; ++k) dst[m][k] = *(const PG8_LAS bf16x8*)(lds + PG8_SA(b, h) + aoff + m * 2048 + k * 1024); } while (0)
; #define PG8_LDB(dst, b, h) do { _Pragma("unroll") for (int n = 0; n < 2; ++n) _Pragma("unroll") for (int k = 0; k < 2; ++k) dst[n][k] = *(const PG8_LAS bf16x8*)(lds + PG8_SB(b, h) + boff + n * 2048 + k * 1024); } while (0)
; #define PG8_MMA(ai, bj, At, Bt) do { __builtin_amdgcn_s_setprio(1); _Pragma("unroll") for (int m = 0; m < 4; ++m) _Pragma("unroll") for (int n = 0; n < 2; ++n) _Pragma("unroll") for (int k = 0; k < 2; ++k) \
;         acc[ai][bj][m][n] = __builtin_amdgcn_mfma_f32_16x16x32_bf16(Bt[n][k], At[m][k], acc[ai][bj][m][n], 0, 0, 0); __builtin_amdgcn_s_setprio(0); } while (0)
; #define PG8_WAIT_V(n) asm volatile("s_waitcnt vmcnt(" #n ")" ::: "memory")
; #define PG8_WAIT_L(n) asm volatile("s_waitcnt lgkmcnt(" #n ")" ::: "memory")
; #define PG8_BAR __builtin_amdgcn_s_barrier()
; #define PG8_SCHED __builtin_amdgcn_sched_barrier(0)
; template <class Epi, class Sched>
; __device__ __forceinline__ void gemm_phase(PG8_LAS unsigned char* lds, const Gemm g, const Sched& S, const Epi& E, const int tid) {
;     ...
;             PG8_STAGE(PG8_SB(0, 1), b2 + hstep, voffB);
;             PG8_WAIT_V(6); PG8_BAR; PG8_MMA(1, 1, At, B1); PG8_BAR;
;             PG8_LDB(B0, 1, 0); PG8_SCHED; PG8_LDA(At, 1, 0); PG8_STAGE(PG8_SA(0, 1), a2 + hstep, voffA);
;             PG8_WAIT_L(8); PG8_BAR; PG8_WAIT_L(0); PG8_MMA(0, 0, At, B0); PG8_BAR; PG8_SCHED;
;             PG8_LDB(B1, 1, 1); PG8_STAGE(PG8_SB(1, 0), b3, voffB);
;             PG8_BAR; PG8_WAIT_L(0); PG8_MMA(0, 1, At, B1); PG8_BAR;
;             PG8_LDA(At, 1, 1); PG8_STAGE(PG8_SA(1, 0), a3, voffA);
;             PG8_BAR; PG8_WAIT_L(0); PG8_MMA(1, 0, At, B0); PG8_BAR; PG8_SCHED;
	s_add_u32 s72, s72, s14
	s_addc_u32 s73, s73, s15
	s_add_i32 s95, s96, s45
	v_lshl_add_u64 v[224:225], s[72:73], 0, v[0:1]
	s_mov_b32 m0, s95
	v_lshl_add_u64 v[226:227], s[72:73], 0, v[142:143]
	global_load_lds_dwordx4 v[224:225], off
	s_add_i32 m0, s95, 0x2000
	s_nop 0
	global_load_lds_dwordx4 v[226:227], off
	s_waitcnt vmcnt(6)
	s_barrier
	s_setprio 1
	v_mfma_f32_16x16x32_bf16 v[50:53], v[188:191], v[152:155], v[50:53]
	v_mfma_f32_16x16x32_bf16 v[46:49], v[200:203], v[152:155], v[46:49]
	v_mfma_f32_16x16x32_bf16 v[34:37], v[188:191], v[164:167], v[34:37]
	v_mfma_f32_16x16x32_bf16 v[30:33], v[200:203], v[164:167], v[30:33]
	v_mfma_f32_16x16x32_bf16 v[18:21], v[188:191], v[172:175], v[18:21]
	v_mfma_f32_16x16x32_bf16 v[14:17], v[200:203], v[172:175], v[14:17]
	v_mfma_f32_16x16x32_bf16 v[6:9], v[188:191], v[180:183], v[6:9]
	v_mfma_f32_16x16x32_bf16 v[2:5], v[200:203], v[180:183], v[2:5]
	v_mfma_f32_16x16x32_bf16 v[50:53], v[192:195], v[160:163], v[50:53]
	v_mfma_f32_16x16x32_bf16 v[46:49], v[216:219], v[160:163], v[46:49]
	v_mfma_f32_16x16x32_bf16 v[34:37], v[192:195], v[168:171], v[34:37]
	v_mfma_f32_16x16x32_bf16 v[30:33], v[216:219], v[168:171], v[30:33]
	v_mfma_f32_16x16x32_bf16 v[18:21], v[192:195], v[176:179], v[18:21]
	v_mfma_f32_16x16x32_bf16 v[14:17], v[216:219], v[176:179], v[14:17]
	v_mfma_f32_16x16x32_bf16 v[6:9], v[192:195], v[184:187], v[6:9]
	v_mfma_f32_16x16x32_bf16 v[2:5], v[216:219], v[184:187], v[2:5]
	s_setprio 0
	s_add_i32 s72, 0, 0x18000
	v_add_u32_e32 v148, s72, v157
	s_barrier
	ds_read_b128 v[130:133], v148
	ds_read_b128 v[134:137], v148 offset:1024
	ds_read_b128 v[138:141], v148 offset:2048
	ds_read_b128 v[148:151], v148 offset:3072
	s_add_u32 s56, s56, s14
	s_addc_u32 s57, s57, s15
	s_mov_b32 m0, s12
	v_lshl_add_u64 v[188:189], s[56:57], 0, v[0:1]
	ds_read_b128 v[152:155], v159 offset:32768
	ds_read_b128 v[160:163], v159 offset:33792
	ds_read_b128 v[164:167], v159 offset:34816
	ds_read_b128 v[168:171], v159 offset:35840
	ds_read_b128 v[172:175], v159 offset:36864
	ds_read_b128 v[176:179], v159 offset:37888
	ds_read_b128 v[180:183], v159 offset:38912
	ds_read_b128 v[184:187], v159 offset:39936
	global_load_lds_dwordx4 v[188:189], off
	v_lshl_add_u64 v[188:189], s[56:57], 0, v[142:143]
	s_mov_b32 m0, s13
	s_nop 0
	global_load_lds_dwordx4 v[188:189], off
	s_waitcnt lgkmcnt(8)
	s_barrier
	s_waitcnt lgkmcnt(0)
	s_setprio 1
	s_waitcnt lgkmcnt(0)
	v_mfma_f32_16x16x32_bf16 v[126:129], v[130:133], v[152:155], v[126:129]
	v_mfma_f32_16x16x32_bf16 v[122:125], v[138:141], v[152:155], v[122:125]
	v_mfma_f32_16x16x32_bf16 v[118:121], v[130:133], v[164:167], v[118:121]
	v_mfma_f32_16x16x32_bf16 v[106:109], v[138:141], v[164:167], v[106:109]
	v_mfma_f32_16x16x32_bf16 v[102:105], v[130:133], v[172:175], v[102:105]
	v_mfma_f32_16x16x32_bf16 v[90:93], v[138:141], v[172:175], v[90:93]
	v_mfma_f32_16x16x32_bf16 v[86:89], v[130:133], v[180:183], v[86:89]
	v_mfma_f32_16x16x32_bf16 v[74:77], v[138:141], v[180:183], v[74:77]
	v_mfma_f32_16x16x32_bf16 v[126:129], v[134:137], v[160:163], v[126:129]
	v_mfma_f32_16x16x32_bf16 v[122:125], v[148:151], v[160:163], v[122:125]
	v_mfma_f32_16x16x32_bf16 v[118:121], v[134:137], v[168:171], v[118:121]
	v_mfma_f32_16x16x32_bf16 v[106:109], v[148:151], v[168:171], v[106:109]
	v_mfma_f32_16x16x32_bf16 v[102:105], v[134:137], v[176:179], v[102:105]
	v_mfma_f32_16x16x32_bf16 v[90:93], v[148:151], v[176:179], v[90:93]
	v_mfma_f32_16x16x32_bf16 v[86:89], v[134:137], v[184:187], v[86:89]
	v_mfma_f32_16x16x32_bf16 v[74:77], v[148:151], v[184:187], v[74:77]
	s_setprio 0
	s_barrier
	s_add_i32 s56, 0, 0x1c000
	s_add_i32 s57, s72, s45
	v_add_u32_e32 v216, s56, v157
	v_lshl_add_u64 v[196:197], v[196:197], 0, s[92:93]
	s_mov_b32 m0, s57
	ds_read_b128 v[188:191], v216
	ds_read_b128 v[192:195], v216 offset:1024
	ds_read_b128 v[200:203], v216 offset:2048
	ds_read_b128 v[216:219], v216 offset:3072
	global_load_lds_dwordx4 v[196:197], off
	v_lshl_add_u64 v[196:197], v[198:199], 0, s[92:93]
	s_add_i32 m0, s57, 0x2000
	s_nop 0
	global_load_lds_dwordx4 v[196:197], off
	s_barrier
	s_waitcnt lgkmcnt(0)
	s_setprio 1
	s_waitcnt lgkmcnt(0)
	v_mfma_f32_16x16x32_bf16 v[114:117], v[188:191], v[152:155], v[114:117]
	v_mfma_f32_16x16x32_bf16 v[110:113], v[200:203], v[152:155], v[110:113]
	v_mfma_f32_16x16x32_bf16 v[98:101], v[188:191], v[164:167], v[98:101]
	v_mfma_f32_16x16x32_bf16 v[94:97], v[200:203], v[164:167], v[94:97]
	v_mfma_f32_16x16x32_bf16 v[82:85], v[188:191], v[172:175], v[82:85]
	v_mfma_f32_16x16x32_bf16 v[78:81], v[200:203], v[172:175], v[78:81]
	v_mfma_f32_16x16x32_bf16 v[70:73], v[188:191], v[180:183], v[70:73]
	v_mfma_f32_16x16x32_bf16 v[66:69], v[200:203], v[180:183], v[66:69]
	v_mfma_f32_16x16x32_bf16 v[114:117], v[192:195], v[160:163], v[114:117]
	v_mfma_f32_16x16x32_bf16 v[110:113], v[216:219], v[160:163], v[110:113]
	v_mfma_f32_16x16x32_bf16 v[98:101], v[192:195], v[168:171], v[98:101]
	v_mfma_f32_16x16x32_bf16 v[94:97], v[216:219], v[168:171], v[94:97]
	v_mfma_f32_16x16x32_bf16 v[82:85], v[192:195], v[176:179], v[82:85]
	v_mfma_f32_16x16x32_bf16 v[78:81], v[216:219], v[176:179], v[78:81]
	v_mfma_f32_16x16x32_bf16 v[70:73], v[192:195], v[184:187], v[70:73]
	v_mfma_f32_16x16x32_bf16 v[66:69], v[216:219], v[184:187], v[66:69]
	s_setprio 0
	s_mov_b32 m0, s64
	v_lshl_add_u64 v[196:197], v[220:221], 0, s[92:93]
	s_barrier
	ds_read_b128 v[152:155], v159 offset:49152
	ds_read_b128 v[160:163], v159 offset:50176
	ds_read_b128 v[164:167], v159 offset:51200
	ds_read_b128 v[168:171], v159 offset:52224
	ds_read_b128 v[172:175], v159 offset:53248
	ds_read_b128 v[176:179], v159 offset:54272
	ds_read_b128 v[180:183], v159 offset:55296
	ds_read_b128 v[184:187], v159 offset:56320
	global_load_lds_dwordx4 v[196:197], off
	v_lshl_add_u64 v[196:197], v[222:223], 0, s[92:93]
	s_mov_b32 m0, s65
	s_nop 0
	global_load_lds_dwordx4 v[196:197], off
	s_barrier
; #define PG8_STAGE(bufoff, gbase, voff) do { _Pragma("unroll") for (int _i = 0; _i < 2; ++_i) \
;         __builtin_amdgcn_global_load_lds((const unsigned*)((const char*)(gbase) + (voff)[_i]), (PG8_LAS unsigned*)(lds + (bufoff) + ldsw + _i * 8192), 16, 0, 0); } while (0)
; #define PG8_LDA(dst, b, h) do { _Pragma("unroll") for (int m = 0; m < 4; ++m) _Pragma("unroll") for (int k = 0; k < 2; ++k) dst[m][k] = *(const PG8_LAS bf16x8*)(lds + PG8_SA(b, h) + aoff + m * 2048 + k * 1024); } while (0)
; #define PG8_WAIT_V(n) asm volatile("s_waitcnt vmcnt(" #n ")" ::: "memory")
; template <class Epi, class Sched>
; __device__ __forceinline__ void gemm_phase(PG8_LAS unsigned char* lds, const Gemm g, const Sched& S, const Epi& E, const int tid) {
;     ...
;             PG8_WAIT_V(6); PG8_BAR; PG8_MMA(1, 1, At, B1); PG8_BAR;
;             PG8_LDB(B0, 1, 0); PG8_SCHED; PG8_LDA(At, 1, 0); PG8_STAGE(PG8_SA(0, 1), a2 + hstep, voffA);
;             PG8_WAIT_L(8); PG8_BAR; PG8_WAIT_L(0); PG8_MMA(0, 0, At, B0); PG8_BAR; PG8_SCHED;
;             PG8_LDB(B1, 1, 1); PG8_STAGE(PG8_SB(1, 0), b3, voffB);
;             PG8_BAR; PG8_WAIT_L(0); PG8_MMA(0, 1, At, B1); PG8_BAR;
;             PG8_LDA(At, 1, 1); PG8_STAGE(PG8_SA(1, 0), a3, voffA);
;             PG8_BAR; PG8_WAIT_L(0); PG8_MMA(1, 0, At, B0); PG8_BAR; PG8_SCHED;
;             PG8_STAGE(PG8_SB(1, 1), b3 + hstep, voffB);
;             PG8_WAIT_V(6); PG8_BAR; PG8_MMA(1, 1, At, B1); PG8_BAR;
;         }
;     __device__ __forceinline__ void operator()(const f32x4 (&acc)[2][2][4][2], const Unit& u, int wr, int wc, int fr, int fq) const {
;         const int row0 = u.pm * BM + wr * 64 + fr, col0 = u.pn * BM + wc * 32 + 4 * fq;
; #pragma unroll
;         for (int ai = 0; ai < 2; ++ai) {
;             f32x4 xv[4][2][2];
; #pragma unroll
;             for (int m = 0; m < 4; ++m)
; #pragma unroll
;                 for (int bj = 0; bj < 2; ++bj)
; #pragma unroll
;                     for (int n = 0; n < 2; ++n) xv[m][bj][n] = *(const f32x4*)(X + (size_t)(row0 + ai * HALF + m * 16) * 1024 + col0 + bj * HALF + n * 16);
; #pragma unroll
;             for (int m = 0; m < 4; ++m)
; #pragma unroll
;                 for (int bj = 0; bj < 2; ++bj)
; #pragma unroll
;                     for (int n = 0; n < 2; ++n) *(f32x4*)(C + (size_t)(row0 + ai * HALF + m * 16) * 1024 + col0 + bj * HALF + n * 16) = xv[m][bj][n] + acc[ai][bj][m][n];
	s_waitcnt lgkmcnt(0)
	s_setprio 1
	s_waitcnt lgkmcnt(0)
	v_mfma_f32_16x16x32_bf16 v[62:65], v[130:133], v[152:155], v[62:65]
	v_mfma_f32_16x16x32_bf16 v[58:61], v[138:141], v[152:155], v[58:61]
	v_mfma_f32_16x16x32_bf16 v[54:57], v[130:133], v[164:167], v[54:57]
	v_mfma_f32_16x16x32_bf16 v[42:45], v[138:141], v[164:167], v[42:45]
	v_mfma_f32_16x16x32_bf16 v[38:41], v[130:133], v[172:175], v[38:41]
	v_mfma_f32_16x16x32_bf16 v[26:29], v[138:141], v[172:175], v[26:29]
	v_mfma_f32_16x16x32_bf16 v[22:25], v[130:133], v[180:183], v[22:25]
	v_mfma_f32_16x16x32_bf16 v[10:13], v[138:141], v[180:183], v[10:13]
	v_mfma_f32_16x16x32_bf16 v[62:65], v[134:137], v[160:163], v[62:65]
	v_mfma_f32_16x16x32_bf16 v[58:61], v[148:151], v[160:163], v[58:61]
	v_mfma_f32_16x16x32_bf16 v[54:57], v[134:137], v[168:171], v[54:57]
	v_mfma_f32_16x16x32_bf16 v[42:45], v[148:151], v[168:171], v[42:45]
	v_mfma_f32_16x16x32_bf16 v[38:41], v[134:137], v[176:179], v[38:41]
	v_mfma_f32_16x16x32_bf16 v[26:29], v[148:151], v[176:179], v[26:29]
	v_mfma_f32_16x16x32_bf16 v[22:25], v[134:137], v[184:187], v[22:25]
	v_mfma_f32_16x16x32_bf16 v[10:13], v[148:151], v[184:187], v[10:13]
	s_setprio 0
	s_barrier
	s_add_i32 s56, s56, s45
	v_lshl_add_u64 v[130:131], v[224:225], 0, s[92:93]
	s_mov_b32 m0, s56
	s_nop 0
	global_load_lds_dwordx4 v[130:131], off
	v_lshl_add_u64 v[130:131], v[226:227], 0, s[92:93]
	s_add_i32 m0, s56, 0x2000
	s_nop 0
	global_load_lds_dwordx4 v[130:131], off
	s_waitcnt vmcnt(6)
	s_barrier
	s_setprio 1
	v_mfma_f32_16x16x32_bf16 v[50:53], v[188:191], v[152:155], v[50:53]
	v_mfma_f32_16x16x32_bf16 v[46:49], v[200:203], v[152:155], v[46:49]
	v_mfma_f32_16x16x32_bf16 v[34:37], v[188:191], v[164:167], v[34:37]
	v_mfma_f32_16x16x32_bf16 v[30:33], v[200:203], v[164:167], v[30:33]
	v_mfma_f32_16x16x32_bf16 v[18:21], v[188:191], v[172:175], v[18:21]
	v_mfma_f32_16x16x32_bf16 v[14:17], v[200:203], v[172:175], v[14:17]
	v_mfma_f32_16x16x32_bf16 v[6:9], v[188:191], v[180:183], v[6:9]
	v_mfma_f32_16x16x32_bf16 v[2:5], v[200:203], v[180:183], v[2:5]
	v_mfma_f32_16x16x32_bf16 v[50:53], v[192:195], v[160:163], v[50:53]
	v_mfma_f32_16x16x32_bf16 v[46:49], v[216:219], v[160:163], v[46:49]
	v_mfma_f32_16x16x32_bf16 v[34:37], v[192:195], v[168:171], v[34:37]
	v_mfma_f32_16x16x32_bf16 v[30:33], v[216:219], v[168:171], v[30:33]
	v_mfma_f32_16x16x32_bf16 v[18:21], v[192:195], v[176:179], v[18:21]
	v_mfma_f32_16x16x32_bf16 v[14:17], v[216:219], v[176:179], v[14:17]
	v_mfma_f32_16x16x32_bf16 v[6:9], v[192:195], v[184:187], v[6:9]
	v_mfma_f32_16x16x32_bf16 v[2:5], v[216:219], v[184:187], v[2:5]
	s_setprio 0
	s_add_u32 s68, s68, 0x100
	s_addc_u32 s69, s69, 0
	s_add_u32 s90, s90, 0x100
	s_addc_u32 s91, s91, 0
	s_cmp_ge_u32 s94, s62
	s_mov_b32 s56, s94
	s_barrier
	s_cbranch_scc0 .LBB0_475
	v_and_b32_e32 v130, 8, v156
	v_sub_u32_e32 v131, v156, v130
	v_lshl_add_u32 v131, s89, 8, v131
	v_lshl_add_u32 v130, v130, 1, v158
	v_lshl_add_u32 v130, s88, 8, v130
	v_lshlrev_b32_e32 v130, 2, v130
	v_lshl_add_u32 v130, v131, 12, v130
	v_mov_b32_e32 v131, 0
	s_mov_b64 s[56:57], 0x8000
	s_mov_b64 s[98:99], 0x80000
	s_sub_u32 s100, s24, s54
	s_subb_u32 s101, s25, s55
	v_lshl_add_u64 v[132:133], v[130:131], 0, s[54:55]
	v_lshl_add_u64 v[134:135], v[132:133], 0, s[56:57]
	global_load_dwordx4 v[160:163], v[132:133], off
	global_load_dwordx4 v[164:167], v[134:135], off
	global_load_dwordx4 v[168:171], v[132:133], off offset:512
	global_load_dwordx4 v[172:175], v[134:135], off offset:512
	v_lshl_add_u64 v[136:137], v[134:135], 0, s[56:57]
	v_lshl_add_u64 v[138:139], v[136:137], 0, s[56:57]
	global_load_dwordx4 v[176:179], v[136:137], off
	global_load_dwordx4 v[180:183], v[138:139], off
	global_load_dwordx4 v[184:187], v[136:137], off offset:512
	global_load_dwordx4 v[188:191], v[138:139], off offset:512
	v_lshl_add_u64 v[140:141], v[138:139], 0, s[56:57]
	v_lshl_add_u64 v[148:149], v[140:141], 0, s[56:57]
	global_load_dwordx4 v[192:195], v[140:141], off
	global_load_dwordx4 v[196:199], v[148:149], off
	global_load_dwordx4 v[200:203], v[140:141], off offset:512
	global_load_dwordx4 v[216:219], v[148:149], off offset:512
	v_lshl_add_u64 v[150:151], v[148:149], 0, s[56:57]
	v_lshl_add_u64 v[152:153], v[150:151], 0, s[56:57]
	global_load_dwordx4 v[220:223], v[150:151], off
	global_load_dwordx4 v[224:227], v[152:153], off
	global_load_dwordx4 v[228:231], v[150:151], off offset:512
	global_load_dwordx4 v[232:235], v[152:153], off offset:512
	s_and_b64 vcc, exec, s[2:3]
	s_mov_b32 s88, s77
	s_mov_b32 s89, s84
	s_mov_b64 s[72:73], s[6:7]
	s_mov_b64 s[68:69], s[4:5]
	v_mov_b32_dpp v236, v122 row_ror:8 row_mask:0xf bank_mask:0xf
	v_mov_b32_dpp v237, v123 row_ror:8 row_mask:0xf bank_mask:0xf
	v_mov_b32_dpp v238, v124 row_ror:8 row_mask:0xf bank_mask:0xf
	v_mov_b32_dpp v239, v125 row_ror:8 row_mask:0xf bank_mask:0xf
	v_mov_b32_dpp v122, v126 row_ror:8 row_mask:0xf bank_mask:0x3
	v_mov_b32_dpp v123, v127 row_ror:8 row_mask:0xf bank_mask:0x3
	v_mov_b32_dpp v124, v128 row_ror:8 row_mask:0xf bank_mask:0x3
	v_mov_b32_dpp v125, v129 row_ror:8 row_mask:0xf bank_mask:0x3
	v_mov_b32_dpp v126, v236 quad_perm:[0,1,2,3] row_mask:0xf bank_mask:0xc
	v_mov_b32_dpp v127, v237 quad_perm:[0,1,2,3] row_mask:0xf bank_mask:0xc
	v_mov_b32_dpp v128, v238 quad_perm:[0,1,2,3] row_mask:0xf bank_mask:0xc
	v_mov_b32_dpp v129, v239 quad_perm:[0,1,2,3] row_mask:0xf bank_mask:0xc
	v_mov_b32_dpp v236, v110 row_ror:8 row_mask:0xf bank_mask:0xf
	v_mov_b32_dpp v237, v111 row_ror:8 row_mask:0xf bank_mask:0xf
	v_mov_b32_dpp v238, v112 row_ror:8 row_mask:0xf bank_mask:0xf
	v_mov_b32_dpp v239, v113 row_ror:8 row_mask:0xf bank_mask:0xf
;     __device__ __forceinline__ void operator()(const f32x4 (&acc)[2][2][4][2], const Unit& u, int wr, int wc, int fr, int fq) const {
;         const int row0 = u.pm * BM + wr * 64 + fr, col0 = u.pn * BM + wc * 32 + 4 * fq;
; #pragma unroll
;         for (int ai = 0; ai < 2; ++ai) {
;             f32x4 xv[4][2][2];
; #pragma unroll
;             for (int m = 0; m < 4; ++m)
; #pragma unroll
;                 for (int bj = 0; bj < 2; ++bj)
; #pragma unroll
;                     for (int n = 0; n < 2; ++n) xv[m][bj][n] = *(const f32x4*)(X + (size_t)(row0 + ai * HALF + m * 16) * 1024 + col0 + bj * HALF + n * 16);
; #pragma unroll
;             for (int m = 0; m < 4; ++m)
; #pragma unroll
;                 for (int bj = 0; bj < 2; ++bj)
; #pragma unroll
;                     for (int n = 0; n < 2; ++n) *(f32x4*)(C + (size_t)(row0 + ai * HALF + m * 16) * 1024 + col0 + bj * HALF + n * 16) = xv[m][bj][n] + acc[ai][bj][m][n];
	v_mov_b32_dpp v110, v114 row_ror:8 row_mask:0xf bank_mask:0x3
	v_mov_b32_dpp v111, v115 row_ror:8 row_mask:0xf bank_mask:0x3
	v_mov_b32_dpp v112, v116 row_ror:8 row_mask:0xf bank_mask:0x3
	v_mov_b32_dpp v113, v117 row_ror:8 row_mask:0xf bank_mask:0x3
	v_mov_b32_dpp v114, v236 quad_perm:[0,1,2,3] row_mask:0xf bank_mask:0xc
	v_mov_b32_dpp v115, v237 quad_perm:[0,1,2,3] row_mask:0xf bank_mask:0xc
	v_mov_b32_dpp v116, v238 quad_perm:[0,1,2,3] row_mask:0xf bank_mask:0xc
	v_mov_b32_dpp v117, v239 quad_perm:[0,1,2,3] row_mask:0xf bank_mask:0xc
	v_mov_b32_dpp v236, v106 row_ror:8 row_mask:0xf bank_mask:0xf
	v_mov_b32_dpp v237, v107 row_ror:8 row_mask:0xf bank_mask:0xf
	v_mov_b32_dpp v238, v108 row_ror:8 row_mask:0xf bank_mask:0xf
	v_mov_b32_dpp v239, v109 row_ror:8 row_mask:0xf bank_mask:0xf
	v_mov_b32_dpp v106, v118 row_ror:8 row_mask:0xf bank_mask:0x3
	v_mov_b32_dpp v107, v119 row_ror:8 row_mask:0xf bank_mask:0x3
	v_mov_b32_dpp v108, v120 row_ror:8 row_mask:0xf bank_mask:0x3
	v_mov_b32_dpp v109, v121 row_ror:8 row_mask:0xf bank_mask:0x3
	v_mov_b32_dpp v118, v236 quad_perm:[0,1,2,3] row_mask:0xf bank_mask:0xc
	v_mov_b32_dpp v119, v237 quad_perm:[0,1,2,3] row_mask:0xf bank_mask:0xc
	v_mov_b32_dpp v120, v238 quad_perm:[0,1,2,3] row_mask:0xf bank_mask:0xc
	v_mov_b32_dpp v121, v239 quad_perm:[0,1,2,3] row_mask:0xf bank_mask:0xc
	v_mov_b32_dpp v236, v94 row_ror:8 row_mask:0xf bank_mask:0xf
	v_mov_b32_dpp v237, v95 row_ror:8 row_mask:0xf bank_mask:0xf
	v_mov_b32_dpp v238, v96 row_ror:8 row_mask:0xf bank_mask:0xf
	v_mov_b32_dpp v239, v97 row_ror:8 row_mask:0xf bank_mask:0xf
	v_mov_b32_dpp v94, v98 row_ror:8 row_mask:0xf bank_mask:0x3
	v_mov_b32_dpp v95, v99 row_ror:8 row_mask:0xf bank_mask:0x3
	v_mov_b32_dpp v96, v100 row_ror:8 row_mask:0xf bank_mask:0x3
	v_mov_b32_dpp v97, v101 row_ror:8 row_mask:0xf bank_mask:0x3
	v_mov_b32_dpp v98, v236 quad_perm:[0,1,2,3] row_mask:0xf bank_mask:0xc
	v_mov_b32_dpp v99, v237 quad_perm:[0,1,2,3] row_mask:0xf bank_mask:0xc
	v_mov_b32_dpp v100, v238 quad_perm:[0,1,2,3] row_mask:0xf bank_mask:0xc
	v_mov_b32_dpp v101, v239 quad_perm:[0,1,2,3] row_mask:0xf bank_mask:0xc
	v_mov_b32_dpp v236, v90 row_ror:8 row_mask:0xf bank_mask:0xf
	v_mov_b32_dpp v237, v91 row_ror:8 row_mask:0xf bank_mask:0xf
	v_mov_b32_dpp v238, v92 row_ror:8 row_mask:0xf bank_mask:0xf
	v_mov_b32_dpp v239, v93 row_ror:8 row_mask:0xf bank_mask:0xf
	v_mov_b32_dpp v90, v102 row_ror:8 row_mask:0xf bank_mask:0x3
	v_mov_b32_dpp v91, v103 row_ror:8 row_mask:0xf bank_mask:0x3
	v_mov_b32_dpp v92, v104 row_ror:8 row_mask:0xf bank_mask:0x3
	v_mov_b32_dpp v93, v105 row_ror:8 row_mask:0xf bank_mask:0x3
	v_mov_b32_dpp v102, v236 quad_perm:[0,1,2,3] row_mask:0xf bank_mask:0xc
	v_mov_b32_dpp v103, v237 quad_perm:[0,1,2,3] row_mask:0xf bank_mask:0xc
	v_mov_b32_dpp v104, v238 quad_perm:[0,1,2,3] row_mask:0xf bank_mask:0xc
	v_mov_b32_dpp v105, v239 quad_perm:[0,1,2,3] row_mask:0xf bank_mask:0xc
	v_mov_b32_dpp v236, v78 row_ror:8 row_mask:0xf bank_mask:0xf
	v_mov_b32_dpp v237, v79 row_ror:8 row_mask:0xf bank_mask:0xf
	v_mov_b32_dpp v238, v80 row_ror:8 row_mask:0xf bank_mask:0xf
	v_mov_b32_dpp v239, v81 row_ror:8 row_mask:0xf bank_mask:0xf
	v_mov_b32_dpp v78, v82 row_ror:8 row_mask:0xf bank_mask:0x3
	v_mov_b32_dpp v79, v83 row_ror:8 row_mask:0xf bank_mask:0x3
	v_mov_b32_dpp v80, v84 row_ror:8 row_mask:0xf bank_mask:0x3
	v_mov_b32_dpp v81, v85 row_ror:8 row_mask:0xf bank_mask:0x3
	v_mov_b32_dpp v82, v236 quad_perm:[0,1,2,3] row_mask:0xf bank_mask:0xc
	v_mov_b32_dpp v83, v237 quad_perm:[0,1,2,3] row_mask:0xf bank_mask:0xc
	v_mov_b32_dpp v84, v238 quad_perm:[0,1,2,3] row_mask:0xf bank_mask:0xc
	v_mov_b32_dpp v85, v239 quad_perm:[0,1,2,3] row_mask:0xf bank_mask:0xc
	v_mov_b32_dpp v236, v74 row_ror:8 row_mask:0xf bank_mask:0xf
	v_mov_b32_dpp v237, v75 row_ror:8 row_mask:0xf bank_mask:0xf
	v_mov_b32_dpp v238, v76 row_ror:8 row_mask:0xf bank_mask:0xf
	v_mov_b32_dpp v239, v77 row_ror:8 row_mask:0xf bank_mask:0xf
	v_mov_b32_dpp v74, v86 row_ror:8 row_mask:0xf bank_mask:0x3
	v_mov_b32_dpp v75, v87 row_ror:8 row_mask:0xf bank_mask:0x3
	v_mov_b32_dpp v76, v88 row_ror:8 row_mask:0xf bank_mask:0x3
	v_mov_b32_dpp v77, v89 row_ror:8 row_mask:0xf bank_mask:0x3
	v_mov_b32_dpp v86, v236 quad_perm:[0,1,2,3] row_mask:0xf bank_mask:0xc
	v_mov_b32_dpp v87, v237 quad_perm:[0,1,2,3] row_mask:0xf bank_mask:0xc
	v_mov_b32_dpp v88, v238 quad_perm:[0,1,2,3] row_mask:0xf bank_mask:0xc
	v_mov_b32_dpp v89, v239 quad_perm:[0,1,2,3] row_mask:0xf bank_mask:0xc
	v_mov_b32_dpp v236, v66 row_ror:8 row_mask:0xf bank_mask:0xf
	v_mov_b32_dpp v237, v67 row_ror:8 row_mask:0xf bank_mask:0xf
	v_mov_b32_dpp v238, v68 row_ror:8 row_mask:0xf bank_mask:0xf
	v_mov_b32_dpp v239, v69 row_ror:8 row_mask:0xf bank_mask:0xf
	v_mov_b32_dpp v66, v70 row_ror:8 row_mask:0xf bank_mask:0x3
	v_mov_b32_dpp v67, v71 row_ror:8 row_mask:0xf bank_mask:0x3
	v_mov_b32_dpp v68, v72 row_ror:8 row_mask:0xf bank_mask:0x3
	v_mov_b32_dpp v69, v73 row_ror:8 row_mask:0xf bank_mask:0x3
	v_mov_b32_dpp v70, v236 quad_perm:[0,1,2,3] row_mask:0xf bank_mask:0xc
	v_mov_b32_dpp v71, v237 quad_perm:[0,1,2,3] row_mask:0xf bank_mask:0xc
	v_mov_b32_dpp v72, v238 quad_perm:[0,1,2,3] row_mask:0xf bank_mask:0xc
	v_mov_b32_dpp v73, v239 quad_perm:[0,1,2,3] row_mask:0xf bank_mask:0xc
	v_mov_b32_dpp v236, v58 row_ror:8 row_mask:0xf bank_mask:0xf
	v_mov_b32_dpp v237, v59 row_ror:8 row_mask:0xf bank_mask:0xf
	v_mov_b32_dpp v238, v60 row_ror:8 row_mask:0xf bank_mask:0xf
	v_mov_b32_dpp v239, v61 row_ror:8 row_mask:0xf bank_mask:0xf
	v_mov_b32_dpp v58, v62 row_ror:8 row_mask:0xf bank_mask:0x3
	v_mov_b32_dpp v59, v63 row_ror:8 row_mask:0xf bank_mask:0x3
;     __device__ __forceinline__ void operator()(const f32x4 (&acc)[2][2][4][2], const Unit& u, int wr, int wc, int fr, int fq) const {
;         const int row0 = u.pm * BM + wr * 64 + fr, col0 = u.pn * BM + wc * 32 + 4 * fq;
; #pragma unroll
;         for (int ai = 0; ai < 2; ++ai) {
;             f32x4 xv[4][2][2];
; #pragma unroll
;             for (int m = 0; m < 4; ++m)
; #pragma unroll
;                 for (int bj = 0; bj < 2; ++bj)
; #pragma unroll
;                     for (int n = 0; n < 2; ++n) xv[m][bj][n] = *(const f32x4*)(X + (size_t)(row0 + ai * HALF + m * 16) * 1024 + col0 + bj * HALF + n * 16);
; #pragma unroll
;             for (int m = 0; m < 4; ++m)
; #pragma unroll
;                 for (int bj = 0; bj < 2; ++bj)
; #pragma unroll
;                     for (int n = 0; n < 2; ++n) *(f32x4*)(C + (size_t)(row0 + ai * HALF + m * 16) * 1024 + col0 + bj * HALF + n * 16) = xv[m][bj][n] + acc[ai][bj][m][n];
	v_mov_b32_dpp v60, v64 row_ror:8 row_mask:0xf bank_mask:0x3
	v_mov_b32_dpp v61, v65 row_ror:8 row_mask:0xf bank_mask:0x3
	v_mov_b32_dpp v62, v236 quad_perm:[0,1,2,3] row_mask:0xf bank_mask:0xc
	v_mov_b32_dpp v63, v237 quad_perm:[0,1,2,3] row_mask:0xf bank_mask:0xc
	v_mov_b32_dpp v64, v238 quad_perm:[0,1,2,3] row_mask:0xf bank_mask:0xc
	v_mov_b32_dpp v65, v239 quad_perm:[0,1,2,3] row_mask:0xf bank_mask:0xc
	v_mov_b32_dpp v236, v46 row_ror:8 row_mask:0xf bank_mask:0xf
	v_mov_b32_dpp v237, v47 row_ror:8 row_mask:0xf bank_mask:0xf
	v_mov_b32_dpp v238, v48 row_ror:8 row_mask:0xf bank_mask:0xf
	v_mov_b32_dpp v239, v49 row_ror:8 row_mask:0xf bank_mask:0xf
	v_mov_b32_dpp v46, v50 row_ror:8 row_mask:0xf bank_mask:0x3
	v_mov_b32_dpp v47, v51 row_ror:8 row_mask:0xf bank_mask:0x3
	v_mov_b32_dpp v48, v52 row_ror:8 row_mask:0xf bank_mask:0x3
	v_mov_b32_dpp v49, v53 row_ror:8 row_mask:0xf bank_mask:0x3
	v_mov_b32_dpp v50, v236 quad_perm:[0,1,2,3] row_mask:0xf bank_mask:0xc
	v_mov_b32_dpp v51, v237 quad_perm:[0,1,2,3] row_mask:0xf bank_mask:0xc
	v_mov_b32_dpp v52, v238 quad_perm:[0,1,2,3] row_mask:0xf bank_mask:0xc
	v_mov_b32_dpp v53, v239 quad_perm:[0,1,2,3] row_mask:0xf bank_mask:0xc
	v_mov_b32_dpp v236, v42 row_ror:8 row_mask:0xf bank_mask:0xf
	v_mov_b32_dpp v237, v43 row_ror:8 row_mask:0xf bank_mask:0xf
	v_mov_b32_dpp v238, v44 row_ror:8 row_mask:0xf bank_mask:0xf
	v_mov_b32_dpp v239, v45 row_ror:8 row_mask:0xf bank_mask:0xf
	v_mov_b32_dpp v42, v54 row_ror:8 row_mask:0xf bank_mask:0x3
	v_mov_b32_dpp v43, v55 row_ror:8 row_mask:0xf bank_mask:0x3
	v_mov_b32_dpp v44, v56 row_ror:8 row_mask:0xf bank_mask:0x3
	v_mov_b32_dpp v45, v57 row_ror:8 row_mask:0xf bank_mask:0x3
	v_mov_b32_dpp v54, v236 quad_perm:[0,1,2,3] row_mask:0xf bank_mask:0xc
	v_mov_b32_dpp v55, v237 quad_perm:[0,1,2,3] row_mask:0xf bank_mask:0xc
	v_mov_b32_dpp v56, v238 quad_perm:[0,1,2,3] row_mask:0xf bank_mask:0xc
	v_mov_b32_dpp v57, v239 quad_perm:[0,1,2,3] row_mask:0xf bank_mask:0xc
	v_mov_b32_dpp v236, v30 row_ror:8 row_mask:0xf bank_mask:0xf
	v_mov_b32_dpp v237, v31 row_ror:8 row_mask:0xf bank_mask:0xf
	v_mov_b32_dpp v238, v32 row_ror:8 row_mask:0xf bank_mask:0xf
	v_mov_b32_dpp v239, v33 row_ror:8 row_mask:0xf bank_mask:0xf
	v_mov_b32_dpp v30, v34 row_ror:8 row_mask:0xf bank_mask:0x3
	v_mov_b32_dpp v31, v35 row_ror:8 row_mask:0xf bank_mask:0x3
	v_mov_b32_dpp v32, v36 row_ror:8 row_mask:0xf bank_mask:0x3
	v_mov_b32_dpp v33, v37 row_ror:8 row_mask:0xf bank_mask:0x3
	v_mov_b32_dpp v34, v236 quad_perm:[0,1,2,3] row_mask:0xf bank_mask:0xc
	v_mov_b32_dpp v35, v237 quad_perm:[0,1,2,3] row_mask:0xf bank_mask:0xc
	v_mov_b32_dpp v36, v238 quad_perm:[0,1,2,3] row_mask:0xf bank_mask:0xc
	v_mov_b32_dpp v37, v239 quad_perm:[0,1,2,3] row_mask:0xf bank_mask:0xc
	v_mov_b32_dpp v236, v26 row_ror:8 row_mask:0xf bank_mask:0xf
	v_mov_b32_dpp v237, v27 row_ror:8 row_mask:0xf bank_mask:0xf
	v_mov_b32_dpp v238, v28 row_ror:8 row_mask:0xf bank_mask:0xf
	v_mov_b32_dpp v239, v29 row_ror:8 row_mask:0xf bank_mask:0xf
	v_mov_b32_dpp v26, v38 row_ror:8 row_mask:0xf bank_mask:0x3
	v_mov_b32_dpp v27, v39 row_ror:8 row_mask:0xf bank_mask:0x3
	v_mov_b32_dpp v28, v40 row_ror:8 row_mask:0xf bank_mask:0x3
	v_mov_b32_dpp v29, v41 row_ror:8 row_mask:0xf bank_mask:0x3
	v_mov_b32_dpp v38, v236 quad_perm:[0,1,2,3] row_mask:0xf bank_mask:0xc
	v_mov_b32_dpp v39, v237 quad_perm:[0,1,2,3] row_mask:0xf bank_mask:0xc
	v_mov_b32_dpp v40, v238 quad_perm:[0,1,2,3] row_mask:0xf bank_mask:0xc
	v_mov_b32_dpp v41, v239 quad_perm:[0,1,2,3] row_mask:0xf bank_mask:0xc
	v_mov_b32_dpp v236, v14 row_ror:8 row_mask:0xf bank_mask:0xf
	v_mov_b32_dpp v237, v15 row_ror:8 row_mask:0xf bank_mask:0xf
	v_mov_b32_dpp v238, v16 row_ror:8 row_mask:0xf bank_mask:0xf
	v_mov_b32_dpp v239, v17 row_ror:8 row_mask:0xf bank_mask:0xf
	v_mov_b32_dpp v14, v18 row_ror:8 row_mask:0xf bank_mask:0x3
	v_mov_b32_dpp v15, v19 row_ror:8 row_mask:0xf bank_mask:0x3
	v_mov_b32_dpp v16, v20 row_ror:8 row_mask:0xf bank_mask:0x3
	v_mov_b32_dpp v17, v21 row_ror:8 row_mask:0xf bank_mask:0x3
	v_mov_b32_dpp v18, v236 quad_perm:[0,1,2,3] row_mask:0xf bank_mask:0xc
	v_mov_b32_dpp v19, v237 quad_perm:[0,1,2,3] row_mask:0xf bank_mask:0xc
	v_mov_b32_dpp v20, v238 quad_perm:[0,1,2,3] row_mask:0xf bank_mask:0xc
	v_mov_b32_dpp v21, v239 quad_perm:[0,1,2,3] row_mask:0xf bank_mask:0xc
	v_mov_b32_dpp v236, v10 row_ror:8 row_mask:0xf bank_mask:0xf
	v_mov_b32_dpp v237, v11 row_ror:8 row_mask:0xf bank_mask:0xf
	v_mov_b32_dpp v238, v12 row_ror:8 row_mask:0xf bank_mask:0xf
	v_mov_b32_dpp v239, v13 row_ror:8 row_mask:0xf bank_mask:0xf
	v_mov_b32_dpp v10, v22 row_ror:8 row_mask:0xf bank_mask:0x3
	v_mov_b32_dpp v11, v23 row_ror:8 row_mask:0xf bank_mask:0x3
	v_mov_b32_dpp v12, v24 row_ror:8 row_mask:0xf bank_mask:0x3
	v_mov_b32_dpp v13, v25 row_ror:8 row_mask:0xf bank_mask:0x3
	v_mov_b32_dpp v22, v236 quad_perm:[0,1,2,3] row_mask:0xf bank_mask:0xc
	v_mov_b32_dpp v23, v237 quad_perm:[0,1,2,3] row_mask:0xf bank_mask:0xc
	v_mov_b32_dpp v24, v238 quad_perm:[0,1,2,3] row_mask:0xf bank_mask:0xc
	v_mov_b32_dpp v25, v239 quad_perm:[0,1,2,3] row_mask:0xf bank_mask:0xc
	v_mov_b32_dpp v236, v2 row_ror:8 row_mask:0xf bank_mask:0xf
	v_mov_b32_dpp v237, v3 row_ror:8 row_mask:0xf bank_mask:0xf
	v_mov_b32_dpp v238, v4 row_ror:8 row_mask:0xf bank_mask:0xf
	v_mov_b32_dpp v239, v5 row_ror:8 row_mask:0xf bank_mask:0xf
	v_mov_b32_dpp v2, v6 row_ror:8 row_mask:0xf bank_mask:0x3
	v_mov_b32_dpp v3, v7 row_ror:8 row_mask:0xf bank_mask:0x3
	v_mov_b32_dpp v4, v8 row_ror:8 row_mask:0xf bank_mask:0x3
	v_mov_b32_dpp v5, v9 row_ror:8 row_mask:0xf bank_mask:0x3
	v_mov_b32_dpp v6, v236 quad_perm:[0,1,2,3] row_mask:0xf bank_mask:0xc
	v_mov_b32_dpp v7, v237 quad_perm:[0,1,2,3] row_mask:0xf bank_mask:0xc
	v_mov_b32_dpp v8, v238 quad_perm:[0,1,2,3] row_mask:0xf bank_mask:0xc
	v_mov_b32_dpp v9, v239 quad_perm:[0,1,2,3] row_mask:0xf bank_mask:0xc
	s_waitcnt vmcnt(12)
;     __device__ __forceinline__ void operator()(const f32x4 (&acc)[2][2][4][2], const Unit& u, int wr, int wc, int fr, int fq) const {
;         const int row0 = u.pm * BM + wr * 64 + fr, col0 = u.pn * BM + wc * 32 + 4 * fq;
; #pragma unroll
;         for (int ai = 0; ai < 2; ++ai) {
;             f32x4 xv[4][2][2];
; #pragma unroll
;             for (int m = 0; m < 4; ++m)
; #pragma unroll
;                 for (int bj = 0; bj < 2; ++bj)
; #pragma unroll
;                     for (int n = 0; n < 2; ++n) xv[m][bj][n] = *(const f32x4*)(X + (size_t)(row0 + ai * HALF + m * 16) * 1024 + col0 + bj * HALF + n * 16);
; #pragma unroll
;             for (int m = 0; m < 4; ++m)
; #pragma unroll
;                 for (int bj = 0; bj < 2; ++bj)
; #pragma unroll
;                     for (int n = 0; n < 2; ++n) *(f32x4*)(C + (size_t)(row0 + ai * HALF + m * 16) * 1024 + col0 + bj * HALF + n * 16) = xv[m][bj][n] + acc[ai][bj][m][n];
	v_pk_add_f32 v[126:127], v[126:127], v[160:161]
	v_pk_add_f32 v[128:129], v[128:129], v[162:163]
	v_pk_add_f32 v[122:123], v[122:123], v[164:165]
	v_pk_add_f32 v[124:125], v[124:125], v[166:167]
	v_pk_add_f32 v[114:115], v[114:115], v[168:169]
	v_pk_add_f32 v[116:117], v[116:117], v[170:171]
	v_pk_add_f32 v[110:111], v[110:111], v[172:173]
	v_pk_add_f32 v[112:113], v[112:113], v[174:175]
	v_lshl_add_u64 v[240:241], v[132:133], 0, s[100:101]
	v_lshl_add_u64 v[246:247], v[134:135], 0, s[100:101]
	global_store_dwordx4 v[240:241], v[126:129], off
	global_store_dwordx4 v[246:247], v[122:125], off
	global_store_dwordx4 v[240:241], v[114:117], off offset:512
	global_store_dwordx4 v[246:247], v[110:113], off offset:512
	v_lshl_add_u64 v[132:133], v[132:133], 0, s[98:99]
	v_lshl_add_u64 v[134:135], v[134:135], 0, s[98:99]
	global_load_dwordx4 v[160:163], v[132:133], off
	global_load_dwordx4 v[164:167], v[134:135], off
	global_load_dwordx4 v[168:171], v[132:133], off offset:512
	global_load_dwordx4 v[172:175], v[134:135], off offset:512
	s_waitcnt vmcnt(16)
	v_pk_add_f32 v[118:119], v[118:119], v[176:177]
	v_pk_add_f32 v[120:121], v[120:121], v[178:179]
	v_pk_add_f32 v[106:107], v[106:107], v[180:181]
	v_pk_add_f32 v[108:109], v[108:109], v[182:183]
	v_pk_add_f32 v[98:99], v[98:99], v[184:185]
	v_pk_add_f32 v[100:101], v[100:101], v[186:187]
	v_pk_add_f32 v[94:95], v[94:95], v[188:189]
	v_pk_add_f32 v[96:97], v[96:97], v[190:191]
	v_lshl_add_u64 v[240:241], v[136:137], 0, s[100:101]
	v_lshl_add_u64 v[246:247], v[138:139], 0, s[100:101]
	global_store_dwordx4 v[240:241], v[118:121], off
	global_store_dwordx4 v[246:247], v[106:109], off
	global_store_dwordx4 v[240:241], v[98:101], off offset:512
	global_store_dwordx4 v[246:247], v[94:97], off offset:512
	v_lshl_add_u64 v[136:137], v[136:137], 0, s[98:99]
	v_lshl_add_u64 v[138:139], v[138:139], 0, s[98:99]
	global_load_dwordx4 v[176:179], v[136:137], off
	global_load_dwordx4 v[180:183], v[138:139], off
	global_load_dwordx4 v[184:187], v[136:137], off offset:512
	global_load_dwordx4 v[188:191], v[138:139], off offset:512
	s_waitcnt vmcnt(20)
	v_pk_add_f32 v[102:103], v[102:103], v[192:193]
	v_pk_add_f32 v[104:105], v[104:105], v[194:195]
	v_pk_add_f32 v[90:91], v[90:91], v[196:197]
	v_pk_add_f32 v[92:93], v[92:93], v[198:199]
	v_pk_add_f32 v[82:83], v[82:83], v[200:201]
	v_pk_add_f32 v[84:85], v[84:85], v[202:203]
	v_pk_add_f32 v[78:79], v[78:79], v[216:217]
	v_pk_add_f32 v[80:81], v[80:81], v[218:219]
	v_lshl_add_u64 v[240:241], v[140:141], 0, s[100:101]
	v_lshl_add_u64 v[246:247], v[148:149], 0, s[100:101]
	global_store_dwordx4 v[240:241], v[102:105], off
	global_store_dwordx4 v[246:247], v[90:93], off
	global_store_dwordx4 v[240:241], v[82:85], off offset:512
	global_store_dwordx4 v[246:247], v[78:81], off offset:512
	v_lshl_add_u64 v[140:141], v[140:141], 0, s[98:99]
	v_lshl_add_u64 v[148:149], v[148:149], 0, s[98:99]
	global_load_dwordx4 v[192:195], v[140:141], off
	global_load_dwordx4 v[196:199], v[148:149], off
	global_load_dwordx4 v[200:203], v[140:141], off offset:512
	global_load_dwordx4 v[216:219], v[148:149], off offset:512
	s_waitcnt vmcnt(24)
	v_pk_add_f32 v[86:87], v[86:87], v[220:221]
	v_pk_add_f32 v[88:89], v[88:89], v[222:223]
	v_pk_add_f32 v[74:75], v[74:75], v[224:225]
	v_pk_add_f32 v[76:77], v[76:77], v[226:227]
	v_pk_add_f32 v[70:71], v[70:71], v[228:229]
	v_pk_add_f32 v[72:73], v[72:73], v[230:231]
	v_pk_add_f32 v[66:67], v[66:67], v[232:233]
	v_pk_add_f32 v[68:69], v[68:69], v[234:235]
	v_lshl_add_u64 v[240:241], v[150:151], 0, s[100:101]
	v_lshl_add_u64 v[246:247], v[152:153], 0, s[100:101]
	global_store_dwordx4 v[240:241], v[86:89], off
	global_store_dwordx4 v[246:247], v[74:77], off
	global_store_dwordx4 v[240:241], v[70:73], off offset:512
	global_store_dwordx4 v[246:247], v[66:69], off offset:512
	v_lshl_add_u64 v[150:151], v[150:151], 0, s[98:99]
	v_lshl_add_u64 v[152:153], v[152:153], 0, s[98:99]
	global_load_dwordx4 v[220:223], v[150:151], off
	global_load_dwordx4 v[224:227], v[152:153], off
	global_load_dwordx4 v[228:231], v[150:151], off offset:512
	global_load_dwordx4 v[232:235], v[152:153], off offset:512
	s_waitcnt vmcnt(24)
	v_pk_add_f32 v[62:63], v[62:63], v[160:161]
	v_pk_add_f32 v[64:65], v[64:65], v[162:163]
	v_pk_add_f32 v[58:59], v[58:59], v[164:165]
	v_pk_add_f32 v[60:61], v[60:61], v[166:167]
	v_pk_add_f32 v[50:51], v[50:51], v[168:169]
	v_pk_add_f32 v[52:53], v[52:53], v[170:171]
	v_pk_add_f32 v[46:47], v[46:47], v[172:173]
	v_pk_add_f32 v[48:49], v[48:49], v[174:175]
	v_lshl_add_u64 v[240:241], v[132:133], 0, s[100:101]
	v_lshl_add_u64 v[246:247], v[134:135], 0, s[100:101]
	global_store_dwordx4 v[240:241], v[62:65], off
	global_store_dwordx4 v[246:247], v[58:61], off
	global_store_dwordx4 v[240:241], v[50:53], off offset:512
	global_store_dwordx4 v[246:247], v[46:49], off offset:512
	s_waitcnt vmcnt(20)
	v_pk_add_f32 v[54:55], v[54:55], v[176:177]
	v_pk_add_f32 v[56:57], v[56:57], v[178:179]
	v_pk_add_f32 v[42:43], v[42:43], v[180:181]
	v_pk_add_f32 v[44:45], v[44:45], v[182:183]
	v_pk_add_f32 v[34:35], v[34:35], v[184:185]
	v_pk_add_f32 v[36:37], v[36:37], v[186:187]
	v_pk_add_f32 v[30:31], v[30:31], v[188:189]
	v_pk_add_f32 v[32:33], v[32:33], v[190:191]
	v_lshl_add_u64 v[240:241], v[136:137], 0, s[100:101]
	v_lshl_add_u64 v[246:247], v[138:139], 0, s[100:101]
	global_store_dwordx4 v[240:241], v[54:57], off
	global_store_dwordx4 v[246:247], v[42:45], off
	global_store_dwordx4 v[240:241], v[34:37], off offset:512
	global_store_dwordx4 v[246:247], v[30:33], off offset:512
	s_waitcnt vmcnt(16)
	v_pk_add_f32 v[38:39], v[38:39], v[192:193]
	v_pk_add_f32 v[40:41], v[40:41], v[194:195]
	v_pk_add_f32 v[26:27], v[26:27], v[196:197]
	v_pk_add_f32 v[28:29], v[28:29], v[198:199]
	v_pk_add_f32 v[18:19], v[18:19], v[200:201]
	v_pk_add_f32 v[20:21], v[20:21], v[202:203]
	v_pk_add_f32 v[14:15], v[14:15], v[216:217]
	v_pk_add_f32 v[16:17], v[16:17], v[218:219]
	v_lshl_add_u64 v[240:241], v[140:141], 0, s[100:101]
	v_lshl_add_u64 v[246:247], v[148:149], 0, s[100:101]
	global_store_dwordx4 v[240:241], v[38:41], off
	global_store_dwordx4 v[246:247], v[26:29], off
	global_store_dwordx4 v[240:241], v[18:21], off offset:512
	global_store_dwordx4 v[246:247], v[14:17], off offset:512
	s_waitcnt vmcnt(12)
	v_pk_add_f32 v[22:23], v[22:23], v[220:221]
	v_pk_add_f32 v[24:25], v[24:25], v[222:223]
	v_pk_add_f32 v[10:11], v[10:11], v[224:225]
	v_pk_add_f32 v[12:13], v[12:13], v[226:227]
	v_pk_add_f32 v[6:7], v[6:7], v[228:229]
	v_pk_add_f32 v[8:9], v[8:9], v[230:231]
	v_pk_add_f32 v[2:3], v[2:3], v[232:233]
	v_pk_add_f32 v[4:5], v[4:5], v[234:235]
	v_lshl_add_u64 v[240:241], v[150:151], 0, s[100:101]
	v_lshl_add_u64 v[246:247], v[152:153], 0, s[100:101]
	global_store_dwordx4 v[240:241], v[22:25], off
	global_store_dwordx4 v[246:247], v[10:13], off
	global_store_dwordx4 v[240:241], v[6:9], off offset:512
	global_store_dwordx4 v[246:247], v[2:5], off offset:512
	s_cbranch_vccz .LBB0_464
; #define PG8_WAIT_V(n) asm volatile("s_waitcnt vmcnt(" #n ")" ::: "memory")
; #define PG8_BAR __builtin_amdgcn_s_barrier()
; template <class Epi, class Sched>
; __device__ __forceinline__ void gemm_phase(PG8_LAS unsigned char* lds, const Gemm g, const Sched& S, const Epi& E, const int tid) {
;     ...
;     PG8_WAIT_V(0);
;     if (wr == 0) PG8_BAR;
;     PG8_BAR;
	s_waitcnt vmcnt(0)
	s_cmpk_gt_u32 s34, 0xff
	s_cbranch_scc1 .LBB0_479
	s_barrier
